# weight-convert loops (P0,P4): per-row gamma loads no longer force vmcnt(0) after each row load; gamma multiply moved to loop top
# speedup vs baseline: 1.0439x; 1.0053x over previous
; __device__ __forceinline__ void cvt_load(const CvtJob& J, f32x4 (&cv)[8], int wave, int lane) {
;     const int nblk = (J.N + 255) / 256, kb = J.item / nblk, nb = J.item % nblk, k0 = 64 * kb, n0 = 256 * nb;
;     const bool nok = (n0 + 4 * lane) < J.N;
; #pragma unroll
;     for (int i = 0; i < 8; ++i) { const int k = k0 + wave + 8 * i;
;         cv[i] = nok ? *(const f32x4*)(J.W + (size_t)k * J.N + n0 + 4 * lane) : (f32x4){0.f, 0.f, 0.f, 0.f};
;         if (J.gam) cv[i] = cv[i] * J.gam[k]; }
.LBB0_39:
	v_cndmask_b32_e64 v0, 0, 1, s[4:5]
	v_cmp_ne_u32_e64 s[2:3], 1, v0
	s_andn2_b64 vcc, exec, s[4:5]
	s_cbranch_vccnz .LBB0_72
	s_add_i32 s4, s76, 0xff
	s_lshr_b32 s4, s4, 8
	s_abs_i32 s5, s4
	v_cvt_f32_u32_e32 v0, s5
	s_sub_i32 s33, 0, s5
	s_abs_i32 s6, s14
	s_xor_b32 s7, s14, s4
	v_rcp_iflag_f32_e32 v0, v0
	s_ashr_i32 s7, s7, 31
	v_lshlrev_b32_e32 v4, 2, v184
	v_lshlrev_b32_e32 v16, 2, v4
	v_mul_f32_e32 v0, 0x4f7ffffe, v0
	v_cvt_u32_f32_e32 v0, v0
	s_nop 0
	v_readfirstlane_b32 s34, v0
	s_mul_i32 s33, s33, s34
	s_mul_hi_u32 s33, s34, s33
	s_add_i32 s34, s34, s33
	s_mul_hi_u32 s33, s6, s34
	s_mul_i32 s34, s33, s5
	s_sub_i32 s6, s6, s34
	s_add_i32 s35, s33, 1
	s_sub_i32 s34, s6, s5
	s_cmp_ge_u32 s6, s5
	s_cselect_b32 s33, s35, s33
	s_cselect_b32 s6, s34, s6
	s_add_i32 s34, s33, 1
	s_cmp_ge_u32 s6, s5
	s_cselect_b32 s5, s34, s33
	s_xor_b32 s5, s5, s7
	s_sub_i32 s5, s5, s7
	s_mul_i32 s4, s5, s4
	s_sub_i32 s4, s14, s4
	s_lshl_b32 s70, s4, 8
	s_lshl_b32 s5, s5, 6
	v_readlane_b32 s6, v238, 37
	v_or_b32_e32 v0, s70, v4
	s_add_i32 s68, s5, s6
	v_cmp_gt_i32_e64 s[4:5], s76, v0
	v_mov_b32_e32 v0, 0
	s_ashr_i32 s71, s70, 31
	v_mov_b32_e32 v1, v0
	v_mov_b32_e32 v2, v0
	v_mov_b32_e32 v3, v0
	v_mov_b32_e32 v70, 1.0
	v_mov_b32_e32 v72, 1.0
	v_mov_b32_e32 v74, 1.0
	v_mov_b32_e32 v76, 1.0
	v_mov_b32_e32 v78, 1.0
	v_mov_b32_e32 v80, 1.0
	v_mov_b32_e32 v82, 1.0
	v_mov_b32_e32 v84, 1.0
	s_and_saveexec_b64 s[6:7], s[4:5]
	s_cbranch_execz .LBB0_42
	s_mul_hi_i32 s35, s68, s76
	s_mul_i32 s34, s68, s76
	s_lshl_b64 s[34:35], s[34:35], 2
	s_add_u32 s33, s0, s34
	s_addc_u32 s69, s1, s35
	s_lshl_b64 s[34:35], s[70:71], 2
	s_add_u32 s34, s33, s34
	s_addc_u32 s35, s69, s35
	global_load_dwordx4 v[0:3], v16, s[34:35]
.LBB0_42:
	s_or_b64 exec, exec, s[6:7]
	s_cmp_lg_u64 s[8:9], 0
	s_cselect_b64 s[72:73], -1, 0
	s_cmp_eq_u64 s[8:9], 0
	s_cbranch_scc1 .LBB0_44
	s_ashr_i32 s69, s68, 31
	s_lshl_b64 s[6:7], s[68:69], 2
	s_add_u32 s6, s8, s6
	s_addc_u32 s7, s9, s7
	v_mov_b32_e32 v4, 0
	global_load_dword v70, v4, s[6:7]
	s_nop 0
	s_nop 0
	s_nop 0

; __device__ __forceinline__ void cvt_load(const CvtJob& J, f32x4 (&cv)[8], int wave, int lane) {
;     ...
;     for (int i = 0; i < 8; ++i) { const int k = k0 + wave + 8 * i;
;         cv[i] = nok ? *(const f32x4*)(J.W + (size_t)k * J.N + n0 + 4 * lane) : (f32x4){0.f, 0.f, 0.f, 0.f};
;         if (J.gam) cv[i] = cv[i] * J.gam[k]; }
.LBB0_46:
	s_or_b64 exec, exec, s[6:7]
	v_cndmask_b32_e64 v8, 0, 1, s[72:73]
	v_cmp_ne_u32_e64 s[6:7], 1, v8
	s_andn2_b64 vcc, exec, s[72:73]
	s_cbranch_vccnz .LBB0_48
	s_ashr_i32 s69, s68, 31
	s_lshl_b64 s[34:35], s[68:69], 2
	s_add_u32 s34, s8, s34
	s_addc_u32 s35, s9, s35
	v_mov_b32_e32 v8, 0
	global_load_dword v72, v8, s[34:35] offset:32
	s_nop 0
	s_nop 0
	s_nop 0

; __device__ __forceinline__ void cvt_load(const CvtJob& J, f32x4 (&cv)[8], int wave, int lane) {
;     ...
;     for (int i = 0; i < 8; ++i) { const int k = k0 + wave + 8 * i;
;         cv[i] = nok ? *(const f32x4*)(J.W + (size_t)k * J.N + n0 + 4 * lane) : (f32x4){0.f, 0.f, 0.f, 0.f};
;         if (J.gam) cv[i] = cv[i] * J.gam[k]; }
.LBB0_50:
	s_or_b64 exec, exec, s[72:73]
	s_and_b64 vcc, exec, s[6:7]
	s_cbranch_vccnz .LBB0_52
	s_ashr_i32 s69, s68, 31
	s_lshl_b64 s[34:35], s[68:69], 2
	s_add_u32 s34, s8, s34
	s_addc_u32 s35, s9, s35
	v_mov_b32_e32 v12, 0
	global_load_dword v74, v12, s[34:35] offset:64
	s_nop 0
	s_nop 0
	s_nop 0

; __device__ __forceinline__ void cvt_load(const CvtJob& J, f32x4 (&cv)[8], int wave, int lane) {
;     ...
;     for (int i = 0; i < 8; ++i) { const int k = k0 + wave + 8 * i;
;         cv[i] = nok ? *(const f32x4*)(J.W + (size_t)k * J.N + n0 + 4 * lane) : (f32x4){0.f, 0.f, 0.f, 0.f};
;         if (J.gam) cv[i] = cv[i] * J.gam[k]; }
.LBB0_54:
	s_or_b64 exec, exec, s[72:73]
	s_and_b64 vcc, exec, s[6:7]
	s_cbranch_vccnz .LBB0_56
	s_ashr_i32 s69, s68, 31
	s_lshl_b64 s[34:35], s[68:69], 2
	s_add_u32 s34, s8, s34
	s_addc_u32 s35, s9, s35
	v_mov_b32_e32 v17, 0
	global_load_dword v76, v17, s[34:35] offset:96
	s_nop 0
	s_nop 0
	s_nop 0

; __device__ __forceinline__ void cvt_load(const CvtJob& J, f32x4 (&cv)[8], int wave, int lane) {
;     ...
;     for (int i = 0; i < 8; ++i) { const int k = k0 + wave + 8 * i;
;         cv[i] = nok ? *(const f32x4*)(J.W + (size_t)k * J.N + n0 + 4 * lane) : (f32x4){0.f, 0.f, 0.f, 0.f};
;         if (J.gam) cv[i] = cv[i] * J.gam[k]; }
.LBB0_58:
	s_or_b64 exec, exec, s[72:73]
	s_and_b64 vcc, exec, s[6:7]
	s_cbranch_vccnz .LBB0_60
	s_ashr_i32 s69, s68, 31
	s_lshl_b64 s[34:35], s[68:69], 2
	s_add_u32 s34, s8, s34
	s_addc_u32 s35, s9, s35
	v_mov_b32_e32 v17, 0
	global_load_dword v78, v17, s[34:35] offset:128
	s_nop 0
	s_nop 0
	s_nop 0

; __device__ __forceinline__ void cvt_load(const CvtJob& J, f32x4 (&cv)[8], int wave, int lane) {
;     ...
;     for (int i = 0; i < 8; ++i) { const int k = k0 + wave + 8 * i;
;         cv[i] = nok ? *(const f32x4*)(J.W + (size_t)k * J.N + n0 + 4 * lane) : (f32x4){0.f, 0.f, 0.f, 0.f};
;         if (J.gam) cv[i] = cv[i] * J.gam[k]; }
.LBB0_62:
	s_or_b64 exec, exec, s[72:73]
	s_and_b64 vcc, exec, s[6:7]
	s_cbranch_vccnz .LBB0_64
	s_ashr_i32 s69, s68, 31
	s_lshl_b64 s[34:35], s[68:69], 2
	s_add_u32 s34, s8, s34
	s_addc_u32 s35, s9, s35
	v_mov_b32_e32 v17, 0
	global_load_dword v80, v17, s[34:35] offset:160
	s_nop 0
	s_nop 0
	s_nop 0

; __device__ __forceinline__ void cvt_load(const CvtJob& J, f32x4 (&cv)[8], int wave, int lane) {
;     ...
;     for (int i = 0; i < 8; ++i) { const int k = k0 + wave + 8 * i;
;         cv[i] = nok ? *(const f32x4*)(J.W + (size_t)k * J.N + n0 + 4 * lane) : (f32x4){0.f, 0.f, 0.f, 0.f};
;         if (J.gam) cv[i] = cv[i] * J.gam[k]; }
.LBB0_66:
	s_or_b64 exec, exec, s[72:73]
	s_and_b64 vcc, exec, s[6:7]
	s_cbranch_vccnz .LBB0_68
	s_ashr_i32 s69, s68, 31
	s_lshl_b64 s[34:35], s[68:69], 2
	s_add_u32 s34, s8, s34
	s_addc_u32 s35, s9, s35
	v_mov_b32_e32 v17, 0
	global_load_dword v82, v17, s[34:35] offset:192
	s_nop 0
	s_nop 0
	s_nop 0

; __device__ __forceinline__ void cvt_load(const CvtJob& J, f32x4 (&cv)[8], int wave, int lane) {
;     ...
;     for (int i = 0; i < 8; ++i) { const int k = k0 + wave + 8 * i;
;         cv[i] = nok ? *(const f32x4*)(J.W + (size_t)k * J.N + n0 + 4 * lane) : (f32x4){0.f, 0.f, 0.f, 0.f};
;         if (J.gam) cv[i] = cv[i] * J.gam[k]; }
.LBB0_70:
	s_or_b64 exec, exec, s[72:73]
	s_and_b64 vcc, exec, s[6:7]
	s_cbranch_vccnz .LBB0_72
	s_ashr_i32 s69, s68, 31
	s_lshl_b64 s[0:1], s[68:69], 2
	s_add_u32 s0, s8, s0
	s_addc_u32 s1, s9, s1
	v_mov_b32_e32 v16, 0
	global_load_dword v84, v16, s[0:1] offset:224
	s_nop 0
	s_nop 0
	s_nop 0

; #define LAS __attribute__((address_space(3)))
; __device__ __forceinline__ void cvt_load(const CvtJob& J, f32x4 (&cv)[8], int wave, int lane) {
;     ...
;     for (int i = 0; i < 8; ++i) { const int k = k0 + wave + 8 * i;
;         cv[i] = nok ? *(const f32x4*)(J.W + (size_t)k * J.N + n0 + 4 * lane) : (f32x4){0.f, 0.f, 0.f, 0.f};
;         if (J.gam) cv[i] = cv[i] * J.gam[k]; }
; }
; __device__ __forceinline__ void cvt_to_lds(const f32x4 (&cv)[8], LAS unsigned char* lds, int wave, int lane) {
; #pragma unroll
;     for (int i = 0; i < 8; ++i) { const int k = wave + 8 * i; *(LAS f32x4*)(lds + (size_t)k * 1024 + (((4 * lane) ^ (4 * (k >> 3))) * 4)) = cv[i]; }
; }
.LBB0_77:
	s_cmpk_lt_i32 s34, 0x2c0
	s_waitcnt vmcnt(0)
	v_pk_mul_f32 v[2:3], v[2:3], v[70:71] op_sel_hi:[1,0]
	v_pk_mul_f32 v[0:1], v[0:1], v[70:71] op_sel_hi:[1,0]
	v_pk_mul_f32 v[6:7], v[6:7], v[72:73] op_sel_hi:[1,0]
	v_pk_mul_f32 v[4:5], v[4:5], v[72:73] op_sel_hi:[1,0]
	v_pk_mul_f32 v[10:11], v[10:11], v[74:75] op_sel_hi:[1,0]
	v_pk_mul_f32 v[8:9], v[8:9], v[74:75] op_sel_hi:[1,0]
	v_pk_mul_f32 v[14:15], v[14:15], v[76:77] op_sel_hi:[1,0]
	v_pk_mul_f32 v[12:13], v[12:13], v[76:77] op_sel_hi:[1,0]
	v_pk_mul_f32 v[22:23], v[22:23], v[78:79] op_sel_hi:[1,0]
	v_pk_mul_f32 v[20:21], v[20:21], v[78:79] op_sel_hi:[1,0]
	v_pk_mul_f32 v[26:27], v[26:27], v[80:81] op_sel_hi:[1,0]
	v_pk_mul_f32 v[24:25], v[24:25], v[80:81] op_sel_hi:[1,0]
	v_pk_mul_f32 v[30:31], v[30:31], v[82:83] op_sel_hi:[1,0]
	v_pk_mul_f32 v[28:29], v[28:29], v[82:83] op_sel_hi:[1,0]
	v_pk_mul_f32 v[34:35], v[34:35], v[84:85] op_sel_hi:[1,0]
	v_pk_mul_f32 v[32:33], v[32:33], v[84:85] op_sel_hi:[1,0]
	v_mov_b32_e32 v70, 1.0
	v_mov_b32_e32 v72, 1.0
	v_mov_b32_e32 v74, 1.0
	v_mov_b32_e32 v76, 1.0
	v_mov_b32_e32 v78, 1.0
	v_mov_b32_e32 v80, 1.0
	v_mov_b32_e32 v82, 1.0
	v_mov_b32_e32 v84, 1.0
	ds_write_b128 v60, v[0:3]
	ds_write_b128 v61, v[4:7]
	ds_write_b128 v62, v[8:11]
	ds_write_b128 v63, v[12:15]
	ds_write_b128 v64, v[20:23]
	ds_write_b128 v65, v[24:27]
	ds_write_b128 v66, v[28:31]
	ds_write_b128 v67, v[32:35]
	s_waitcnt lgkmcnt(0)
	s_barrier
	s_cbranch_scc1 .LBB0_80
	s_add_i32 s8, s34, 0xfffffd40
	s_cmpk_lt_u32 s8, 0x2c0
	s_cselect_b64 s[6:7], -1, 0
	s_add_i32 s9, s34, 0xfffffa80
	s_and_b64 s[4:5], s[6:7], exec
	s_cselect_b32 s3, s63, s3
	s_cselect_b32 s2, s62, s2
	s_cselect_b32 s1, s87, s1
	s_cselect_b32 s0, s86, s0
	s_cselect_b32 s93, 0, s93
	s_cselect_b32 s92, 0, s92
	s_cselect_b32 s95, 0x800, s95
	s_cselect_b32 s97, 0x1600, s97
	s_cselect_b32 s79, 2, s79
	s_cselect_b32 s33, s8, s33
	s_cselect_b32 s8, s8, s9
	s_mov_b64 s[4:5], -1
	s_and_b64 vcc, exec, s[6:7]
	s_cbranch_vccz .LBB0_81

; __device__ __forceinline__ void cvt_load(const CvtJob& J, f32x4 (&cv)[8], int wave, int lane) {
;     ...
;     for (int i = 0; i < 8; ++i) { const int k = k0 + wave + 8 * i;
;         cv[i] = nok ? *(const f32x4*)(J.W + (size_t)k * J.N + n0 + 4 * lane) : (f32x4){0.f, 0.f, 0.f, 0.f};
;         if (J.gam) cv[i] = cv[i] * J.gam[k]; }
.LBB0_101:
	s_or_b64 exec, exec, s[8:9]
	s_cmp_lg_u64 s[92:93], 0
	s_cselect_b64 s[72:73], -1, 0
	s_cmp_eq_u64 s[92:93], 0
	s_cbranch_scc1 .LBB0_103
	s_ashr_i32 s69, s68, 31
	s_lshl_b64 s[8:9], s[68:69], 2
	s_add_u32 s8, s92, s8
	s_addc_u32 s9, s93, s9
	global_load_dword v70, v16, s[8:9]
	s_nop 0
	s_nop 0
	s_nop 0

; __device__ __forceinline__ void cvt_load(const CvtJob& J, f32x4 (&cv)[8], int wave, int lane) {
;     ...
;     for (int i = 0; i < 8; ++i) { const int k = k0 + wave + 8 * i;
;         cv[i] = nok ? *(const f32x4*)(J.W + (size_t)k * J.N + n0 + 4 * lane) : (f32x4){0.f, 0.f, 0.f, 0.f};
;         if (J.gam) cv[i] = cv[i] * J.gam[k]; }
.LBB0_105:
	s_or_b64 exec, exec, s[8:9]
	v_cndmask_b32_e64 v8, 0, 1, s[72:73]
	v_cmp_ne_u32_e64 s[8:9], 1, v8
	s_andn2_b64 vcc, exec, s[72:73]
	s_cbranch_vccnz .LBB0_107
	s_ashr_i32 s69, s68, 31
	s_lshl_b64 s[72:73], s[68:69], 2
	s_add_u32 s72, s92, s72
	s_addc_u32 s73, s93, s73
	global_load_dword v72, v16, s[72:73] offset:32
	s_nop 0
	s_nop 0
	s_nop 0

; __device__ __forceinline__ void cvt_load(const CvtJob& J, f32x4 (&cv)[8], int wave, int lane) {
;     ...
;     for (int i = 0; i < 8; ++i) { const int k = k0 + wave + 8 * i;
;         cv[i] = nok ? *(const f32x4*)(J.W + (size_t)k * J.N + n0 + 4 * lane) : (f32x4){0.f, 0.f, 0.f, 0.f};
;         if (J.gam) cv[i] = cv[i] * J.gam[k]; }
.LBB0_109:
	s_or_b64 exec, exec, s[72:73]
	s_and_b64 vcc, exec, s[8:9]
	s_cbranch_vccnz .LBB0_111
	s_ashr_i32 s69, s68, 31
	s_lshl_b64 s[72:73], s[68:69], 2
	s_add_u32 s72, s92, s72
	s_addc_u32 s73, s93, s73
	global_load_dword v74, v16, s[72:73] offset:64
	s_nop 0
	s_nop 0
	s_nop 0

; __device__ __forceinline__ void cvt_load(const CvtJob& J, f32x4 (&cv)[8], int wave, int lane) {
;     ...
;     for (int i = 0; i < 8; ++i) { const int k = k0 + wave + 8 * i;
;         cv[i] = nok ? *(const f32x4*)(J.W + (size_t)k * J.N + n0 + 4 * lane) : (f32x4){0.f, 0.f, 0.f, 0.f};
;         if (J.gam) cv[i] = cv[i] * J.gam[k]; }
.LBB0_113:
	s_or_b64 exec, exec, s[72:73]
	s_and_b64 vcc, exec, s[8:9]
	s_cbranch_vccnz .LBB0_115
	s_ashr_i32 s69, s68, 31
	s_lshl_b64 s[72:73], s[68:69], 2
	s_add_u32 s72, s92, s72
	s_addc_u32 s73, s93, s73
	global_load_dword v76, v16, s[72:73] offset:96
	s_nop 0
	s_nop 0
	s_nop 0

; __device__ __forceinline__ void cvt_load(const CvtJob& J, f32x4 (&cv)[8], int wave, int lane) {
;     ...
;     for (int i = 0; i < 8; ++i) { const int k = k0 + wave + 8 * i;
;         cv[i] = nok ? *(const f32x4*)(J.W + (size_t)k * J.N + n0 + 4 * lane) : (f32x4){0.f, 0.f, 0.f, 0.f};
;         if (J.gam) cv[i] = cv[i] * J.gam[k]; }
.LBB0_117:
	s_or_b64 exec, exec, s[72:73]
	s_and_b64 vcc, exec, s[8:9]
	s_cbranch_vccnz .LBB0_119
	s_ashr_i32 s69, s68, 31
	s_lshl_b64 s[72:73], s[68:69], 2
	s_add_u32 s72, s92, s72
	s_addc_u32 s73, s93, s73
	global_load_dword v78, v16, s[72:73] offset:128
	s_nop 0
	s_nop 0
	s_nop 0

; __device__ __forceinline__ void cvt_load(const CvtJob& J, f32x4 (&cv)[8], int wave, int lane) {
;     ...
;     for (int i = 0; i < 8; ++i) { const int k = k0 + wave + 8 * i;
;         cv[i] = nok ? *(const f32x4*)(J.W + (size_t)k * J.N + n0 + 4 * lane) : (f32x4){0.f, 0.f, 0.f, 0.f};
;         if (J.gam) cv[i] = cv[i] * J.gam[k]; }
.LBB0_121:
	s_or_b64 exec, exec, s[72:73]
	s_and_b64 vcc, exec, s[8:9]
	s_cbranch_vccnz .LBB0_123
	s_ashr_i32 s69, s68, 31
	s_lshl_b64 s[72:73], s[68:69], 2
	s_add_u32 s72, s92, s72
	s_addc_u32 s73, s93, s73
	global_load_dword v80, v16, s[72:73] offset:160
	s_nop 0
	s_nop 0
	s_nop 0

; __device__ __forceinline__ void cvt_load(const CvtJob& J, f32x4 (&cv)[8], int wave, int lane) {
;     ...
;     for (int i = 0; i < 8; ++i) { const int k = k0 + wave + 8 * i;
;         cv[i] = nok ? *(const f32x4*)(J.W + (size_t)k * J.N + n0 + 4 * lane) : (f32x4){0.f, 0.f, 0.f, 0.f};
;         if (J.gam) cv[i] = cv[i] * J.gam[k]; }
.LBB0_125:
	s_or_b64 exec, exec, s[72:73]
	s_and_b64 vcc, exec, s[8:9]
	s_cbranch_vccnz .LBB0_127
	s_ashr_i32 s69, s68, 31
	s_lshl_b64 s[72:73], s[68:69], 2
	s_add_u32 s72, s92, s72
	s_addc_u32 s73, s93, s73
	global_load_dword v82, v16, s[72:73] offset:192
	s_nop 0
	s_nop 0
	s_nop 0

; __device__ __forceinline__ void cvt_load(const CvtJob& J, f32x4 (&cv)[8], int wave, int lane) {
;     ...
;     for (int i = 0; i < 8; ++i) { const int k = k0 + wave + 8 * i;
;         cv[i] = nok ? *(const f32x4*)(J.W + (size_t)k * J.N + n0 + 4 * lane) : (f32x4){0.f, 0.f, 0.f, 0.f};
;         if (J.gam) cv[i] = cv[i] * J.gam[k]; }
.LBB0_129:
	s_or_b64 exec, exec, s[72:73]
	s_and_b64 vcc, exec, s[8:9]
	s_cbranch_vccnz .LBB0_131
	s_ashr_i32 s69, s68, 31
	s_lshl_b64 s[6:7], s[68:69], 2
	s_add_u32 s6, s92, s6
	s_addc_u32 s7, s93, s7
	global_load_dword v84, v16, s[6:7] offset:224
	s_nop 0
	s_nop 0
	s_nop 0

; __device__ __forceinline__ void cvt_load(const CvtJob& J, f32x4 (&cv)[8], int wave, int lane) {
;     const int nblk = (J.N + 255) / 256, kb = J.item / nblk, nb = J.item % nblk, k0 = 64 * kb, n0 = 256 * nb;
;     const bool nok = (n0 + 4 * lane) < J.N;
; #pragma unroll
;     for (int i = 0; i < 8; ++i) { const int k = k0 + wave + 8 * i;
;         cv[i] = nok ? *(const f32x4*)(J.W + (size_t)k * J.N + n0 + 4 * lane) : (f32x4){0.f, 0.f, 0.f, 0.f};
;         if (J.gam) cv[i] = cv[i] * J.gam[k]; }
.LBB0_615:
	v_cndmask_b32_e64 v0, 0, 1, s[8:9]
	s_mov_b32 s81, s10
	v_cmp_ne_u32_e64 s[6:7], 1, v0
	s_andn2_b64 vcc, exec, s[8:9]
	s_cbranch_vccnz .LBB0_648
	s_add_i32 s8, s82, 0xff
	s_ashr_i32 s9, s8, 31
	s_lshr_b32 s9, s9, 24
	s_add_i32 s8, s8, s9
	s_ashr_i32 s8, s8, 8
	s_abs_i32 s9, s8
	v_cvt_f32_u32_e32 v0, s9
	s_sub_i32 s16, 0, s9
	s_abs_i32 s10, s14
	s_xor_b32 s11, s14, s8
	v_rcp_iflag_f32_e32 v0, v0
	s_ashr_i32 s11, s11, 31
	s_waitcnt vmcnt(0)
	v_mov_b32_e32 v2, 0
	v_mov_b32_e32 v3, v2
	v_mul_f32_e32 v0, 0x4f7ffffe, v0
	v_cvt_u32_f32_e32 v0, v0
	v_mov_b32_e32 v4, v2
	v_mov_b32_e32 v5, v2
	v_readfirstlane_b32 s17, v0
	s_mul_i32 s16, s16, s17
	s_mul_hi_u32 s16, s17, s16
	s_add_i32 s17, s17, s16
	s_mul_hi_u32 s16, s10, s17
	s_mul_i32 s17, s16, s9
	s_sub_i32 s10, s10, s17
	s_add_i32 s33, s16, 1
	s_sub_i32 s17, s10, s9
	s_cmp_ge_u32 s10, s9
	s_cselect_b32 s16, s33, s16
	s_cselect_b32 s10, s17, s10
	s_add_i32 s17, s16, 1
	s_cmp_ge_u32 s10, s9
	s_cselect_b32 s9, s17, s16
	s_xor_b32 s9, s9, s11
	s_sub_i32 s9, s9, s11
	s_mul_i32 s8, s9, s8
	s_sub_i32 s8, s14, s8
	s_lshl_b32 s64, s8, 8
	s_lshl_b32 s9, s9, 6
	v_or_b32_e32 v0, s64, v34
	s_add_i32 s62, s9, s90
	s_ashr_i32 s65, s64, 31
	v_cmp_gt_i32_e64 s[8:9], s82, v0
	v_mov_b32_e32 v70, 1.0
	v_mov_b32_e32 v72, 1.0
	v_mov_b32_e32 v74, 1.0
	v_mov_b32_e32 v76, 1.0
	v_mov_b32_e32 v78, 1.0
	v_mov_b32_e32 v80, 1.0
	v_mov_b32_e32 v82, 1.0
	v_mov_b32_e32 v84, 1.0
	s_and_saveexec_b64 s[10:11], s[8:9]
	s_cbranch_execz .LBB0_618
	s_ashr_i32 s16, s62, 31
	s_mul_hi_u32 s17, s62, s82
	s_mul_i32 s16, s16, s82
	s_add_i32 s17, s17, s16
	s_mul_i32 s16, s62, s82
	s_lshl_b64 s[16:17], s[16:17], 2
	s_add_u32 s33, s60, s16
	s_addc_u32 s34, s61, s17
	s_lshl_b64 s[16:17], s[64:65], 2
	s_add_u32 s16, s33, s16
	s_addc_u32 s17, s34, s17
	v_lshlrev_b32_e32 v0, 2, v34
	global_load_dwordx4 v[2:5], v0, s[16:17]
.LBB0_618:
	s_or_b64 exec, exec, s[10:11]
	s_cmp_lg_u64 s[12:13], 0
	s_cselect_b64 s[66:67], -1, 0
	s_cmp_eq_u64 s[12:13], 0
	s_cbranch_scc1 .LBB0_620
	s_ashr_i32 s63, s62, 31
	s_lshl_b64 s[10:11], s[62:63], 2
	s_add_u32 s10, s12, s10
	s_addc_u32 s11, s13, s11
	global_load_dword v70, v1, s[10:11]
	s_nop 0
	s_nop 0
	s_nop 0

; __device__ __forceinline__ void cvt_load(const CvtJob& J, f32x4 (&cv)[8], int wave, int lane) {
;     ...
;     for (int i = 0; i < 8; ++i) { const int k = k0 + wave + 8 * i;
;         cv[i] = nok ? *(const f32x4*)(J.W + (size_t)k * J.N + n0 + 4 * lane) : (f32x4){0.f, 0.f, 0.f, 0.f};
;         if (J.gam) cv[i] = cv[i] * J.gam[k]; }
.LBB0_622:
	s_or_b64 exec, exec, s[10:11]
	v_cndmask_b32_e64 v0, 0, 1, s[66:67]
	v_cmp_ne_u32_e64 s[10:11], 1, v0
	s_andn2_b64 vcc, exec, s[66:67]
	s_cbranch_vccnz .LBB0_624
	s_ashr_i32 s63, s62, 31
	s_lshl_b64 s[16:17], s[62:63], 2
	s_add_u32 s16, s12, s16
	s_addc_u32 s17, s13, s17
	global_load_dword v72, v1, s[16:17] offset:32
	s_nop 0
	s_nop 0
	s_nop 0

; __device__ __forceinline__ void cvt_load(const CvtJob& J, f32x4 (&cv)[8], int wave, int lane) {
;     ...
;     for (int i = 0; i < 8; ++i) { const int k = k0 + wave + 8 * i;
;         cv[i] = nok ? *(const f32x4*)(J.W + (size_t)k * J.N + n0 + 4 * lane) : (f32x4){0.f, 0.f, 0.f, 0.f};
;         if (J.gam) cv[i] = cv[i] * J.gam[k]; }
.LBB0_626:
	s_or_b64 exec, exec, s[66:67]
	s_and_b64 vcc, exec, s[10:11]
	s_cbranch_vccnz .LBB0_628
	s_ashr_i32 s63, s62, 31
	s_lshl_b64 s[16:17], s[62:63], 2
	s_add_u32 s16, s12, s16
	s_addc_u32 s17, s13, s17
	global_load_dword v74, v1, s[16:17] offset:64
	s_nop 0
	s_nop 0
	s_nop 0

; __device__ __forceinline__ void cvt_load(const CvtJob& J, f32x4 (&cv)[8], int wave, int lane) {
;     ...
;     for (int i = 0; i < 8; ++i) { const int k = k0 + wave + 8 * i;
;         cv[i] = nok ? *(const f32x4*)(J.W + (size_t)k * J.N + n0 + 4 * lane) : (f32x4){0.f, 0.f, 0.f, 0.f};
;         if (J.gam) cv[i] = cv[i] * J.gam[k]; }
.LBB0_630:
	s_or_b64 exec, exec, s[66:67]
	s_and_b64 vcc, exec, s[10:11]
	s_cbranch_vccnz .LBB0_632
	s_ashr_i32 s63, s62, 31
	s_lshl_b64 s[16:17], s[62:63], 2
	s_add_u32 s16, s12, s16
	s_addc_u32 s17, s13, s17
	global_load_dword v76, v1, s[16:17] offset:96
	s_nop 0
	s_nop 0
	s_nop 0

; __device__ __forceinline__ void cvt_load(const CvtJob& J, f32x4 (&cv)[8], int wave, int lane) {
;     ...
;     for (int i = 0; i < 8; ++i) { const int k = k0 + wave + 8 * i;
;         cv[i] = nok ? *(const f32x4*)(J.W + (size_t)k * J.N + n0 + 4 * lane) : (f32x4){0.f, 0.f, 0.f, 0.f};
;         if (J.gam) cv[i] = cv[i] * J.gam[k]; }
.LBB0_634:
	s_or_b64 exec, exec, s[66:67]
	s_and_b64 vcc, exec, s[10:11]
	s_cbranch_vccnz .LBB0_636
	s_ashr_i32 s63, s62, 31
	s_lshl_b64 s[16:17], s[62:63], 2
	s_add_u32 s16, s12, s16
	s_addc_u32 s17, s13, s17
	global_load_dword v78, v1, s[16:17] offset:128
	s_nop 0
	s_nop 0
	s_nop 0

; __device__ __forceinline__ void cvt_load(const CvtJob& J, f32x4 (&cv)[8], int wave, int lane) {
;     ...
;     for (int i = 0; i < 8; ++i) { const int k = k0 + wave + 8 * i;
;         cv[i] = nok ? *(const f32x4*)(J.W + (size_t)k * J.N + n0 + 4 * lane) : (f32x4){0.f, 0.f, 0.f, 0.f};
;         if (J.gam) cv[i] = cv[i] * J.gam[k]; }
.LBB0_638:
	s_or_b64 exec, exec, s[66:67]
	s_and_b64 vcc, exec, s[10:11]
	s_cbranch_vccnz .LBB0_640
	s_ashr_i32 s63, s62, 31
	s_lshl_b64 s[16:17], s[62:63], 2
	s_add_u32 s16, s12, s16
	s_addc_u32 s17, s13, s17
	global_load_dword v80, v1, s[16:17] offset:160
	s_nop 0
	s_nop 0
	s_nop 0

; __device__ __forceinline__ void cvt_load(const CvtJob& J, f32x4 (&cv)[8], int wave, int lane) {
;     ...
;     for (int i = 0; i < 8; ++i) { const int k = k0 + wave + 8 * i;
;         cv[i] = nok ? *(const f32x4*)(J.W + (size_t)k * J.N + n0 + 4 * lane) : (f32x4){0.f, 0.f, 0.f, 0.f};
;         if (J.gam) cv[i] = cv[i] * J.gam[k]; }
.LBB0_642:
	s_or_b64 exec, exec, s[66:67]
	s_and_b64 vcc, exec, s[10:11]
	s_cbranch_vccnz .LBB0_644
	s_ashr_i32 s63, s62, 31
	s_lshl_b64 s[16:17], s[62:63], 2
	s_add_u32 s16, s12, s16
	s_addc_u32 s17, s13, s17
	global_load_dword v82, v1, s[16:17] offset:192
	s_nop 0
	s_nop 0
	s_nop 0

; __device__ __forceinline__ void cvt_load(const CvtJob& J, f32x4 (&cv)[8], int wave, int lane) {
;     ...
;     for (int i = 0; i < 8; ++i) { const int k = k0 + wave + 8 * i;
;         cv[i] = nok ? *(const f32x4*)(J.W + (size_t)k * J.N + n0 + 4 * lane) : (f32x4){0.f, 0.f, 0.f, 0.f};
;         if (J.gam) cv[i] = cv[i] * J.gam[k]; }
.LBB0_646:
	s_or_b64 exec, exec, s[66:67]
	s_and_b64 vcc, exec, s[10:11]
	s_cbranch_vccnz .LBB0_648
	s_ashr_i32 s63, s62, 31
	s_lshl_b64 s[8:9], s[62:63], 2
	s_add_u32 s8, s12, s8
	s_addc_u32 s9, s13, s9
	global_load_dword v84, v1, s[8:9] offset:224
	s_nop 0
	s_nop 0
	s_nop 0

; #define LAS __attribute__((address_space(3)))
; __device__ __forceinline__ void cvt_load(const CvtJob& J, f32x4 (&cv)[8], int wave, int lane) {
;     ...
;     for (int i = 0; i < 8; ++i) { const int k = k0 + wave + 8 * i;
;         cv[i] = nok ? *(const f32x4*)(J.W + (size_t)k * J.N + n0 + 4 * lane) : (f32x4){0.f, 0.f, 0.f, 0.f};
;         if (J.gam) cv[i] = cv[i] * J.gam[k]; }
; }
; __device__ __forceinline__ void cvt_to_lds(const f32x4 (&cv)[8], LAS unsigned char* lds, int wave, int lane) {
; #pragma unroll
;     for (int i = 0; i < 8; ++i) { const int k = wave + 8 * i; *(LAS f32x4*)(lds + (size_t)k * 1024 + (((4 * lane) ^ (4 * (k >> 3))) * 4)) = cv[i]; }
; }
.LBB0_649:
	s_cmpk_lt_i32 s16, 0x2c0
	s_mov_b64 s[6:7], -1
	s_waitcnt vmcnt(0)
	v_pk_mul_f32 v[4:5], v[4:5], v[70:71] op_sel_hi:[1,0]
	v_pk_mul_f32 v[2:3], v[2:3], v[70:71] op_sel_hi:[1,0]
	v_pk_mul_f32 v[8:9], v[8:9], v[72:73] op_sel_hi:[1,0]
	v_pk_mul_f32 v[6:7], v[6:7], v[72:73] op_sel_hi:[1,0]
	v_pk_mul_f32 v[12:13], v[12:13], v[74:75] op_sel_hi:[1,0]
	v_pk_mul_f32 v[10:11], v[10:11], v[74:75] op_sel_hi:[1,0]
	v_pk_mul_f32 v[16:17], v[16:17], v[76:77] op_sel_hi:[1,0]
	v_pk_mul_f32 v[14:15], v[14:15], v[76:77] op_sel_hi:[1,0]
	v_pk_mul_f32 v[20:21], v[20:21], v[78:79] op_sel_hi:[1,0]
	v_pk_mul_f32 v[18:19], v[18:19], v[78:79] op_sel_hi:[1,0]
	v_pk_mul_f32 v[24:25], v[24:25], v[80:81] op_sel_hi:[1,0]
	v_pk_mul_f32 v[22:23], v[22:23], v[80:81] op_sel_hi:[1,0]
	v_pk_mul_f32 v[28:29], v[28:29], v[82:83] op_sel_hi:[1,0]
	v_pk_mul_f32 v[26:27], v[26:27], v[82:83] op_sel_hi:[1,0]
	v_pk_mul_f32 v[32:33], v[32:33], v[84:85] op_sel_hi:[1,0]
	v_pk_mul_f32 v[30:31], v[30:31], v[84:85] op_sel_hi:[1,0]
	v_mov_b32_e32 v70, 1.0
	v_mov_b32_e32 v72, 1.0
	v_mov_b32_e32 v74, 1.0
	v_mov_b32_e32 v76, 1.0
	v_mov_b32_e32 v78, 1.0
	v_mov_b32_e32 v80, 1.0
	v_mov_b32_e32 v82, 1.0
	v_mov_b32_e32 v84, 1.0
	ds_write_b128 v60, v[2:5]
	ds_write_b128 v61, v[6:9]
	ds_write_b128 v62, v[10:13]
	ds_write_b128 v63, v[14:17]
	ds_write_b128 v64, v[18:21]
	ds_write_b128 v65, v[22:25]
	ds_write_b128 v66, v[26:29]
	ds_write_b128 v67, v[30:33]
	s_waitcnt lgkmcnt(0)
	s_barrier
	s_cbranch_scc1 .LBB0_651
	s_add_i32 s12, s16, 0xfffffd40
	s_cmpk_lt_u32 s12, 0x2c0
	s_cselect_b64 s[8:9], -1, 0
	s_add_i32 s13, s16, 0xfffffa80
	s_and_b64 s[10:11], s[8:9], exec
	s_cselect_b32 s55, s27, s55
	s_cselect_b32 s54, s26, s54
	s_cselect_b32 s53, s87, s53
	s_cselect_b32 s52, s86, s52
	s_cselect_b32 s45, s23, s45
	s_cselect_b32 s44, s22, s44
	s_cselect_b32 s77, 0x800, s77
	s_cselect_b32 s76, 0x1600, s76
	s_cselect_b32 s75, 2, s75
	s_cselect_b32 s78, s12, s78
	s_cselect_b32 s10, s12, s13
	s_and_b64 vcc, exec, s[8:9]
	s_cbranch_vccz .LBB0_652
	s_branch .LBB0_654

; __device__ __forceinline__ void cvt_load(const CvtJob& J, f32x4 (&cv)[8], int wave, int lane) {
;     ...
;     for (int i = 0; i < 8; ++i) { const int k = k0 + wave + 8 * i;
;         cv[i] = nok ? *(const f32x4*)(J.W + (size_t)k * J.N + n0 + 4 * lane) : (f32x4){0.f, 0.f, 0.f, 0.f};
;         if (J.gam) cv[i] = cv[i] * J.gam[k]; }
.LBB0_657:
	s_or_b64 exec, exec, s[8:9]
	s_cmp_lg_u64 s[44:45], 0
	s_cselect_b64 s[62:63], -1, 0
	s_cmp_eq_u64 s[44:45], 0
	s_cbranch_scc1 .LBB0_659
	s_ashr_i32 s13, s12, 31
	s_lshl_b64 s[8:9], s[12:13], 2
	s_add_u32 s8, s44, s8
	s_addc_u32 s9, s45, s9
	global_load_dword v70, v1, s[8:9]
	s_nop 0
	s_nop 0
	s_nop 0

; __device__ __forceinline__ void cvt_load(const CvtJob& J, f32x4 (&cv)[8], int wave, int lane) {
;     ...
;     for (int i = 0; i < 8; ++i) { const int k = k0 + wave + 8 * i;
;         cv[i] = nok ? *(const f32x4*)(J.W + (size_t)k * J.N + n0 + 4 * lane) : (f32x4){0.f, 0.f, 0.f, 0.f};
;         if (J.gam) cv[i] = cv[i] * J.gam[k]; }
.LBB0_661:
	s_or_b64 exec, exec, s[8:9]
	v_cndmask_b32_e64 v10, 0, 1, s[62:63]
	v_cmp_ne_u32_e64 s[8:9], 1, v10
	s_andn2_b64 vcc, exec, s[62:63]
	s_cbranch_vccnz .LBB0_663
	s_ashr_i32 s13, s12, 31
	s_lshl_b64 s[34:35], s[12:13], 2
	s_add_u32 s34, s44, s34
	s_addc_u32 s35, s45, s35
	global_load_dword v72, v1, s[34:35] offset:32
	s_nop 0
	s_nop 0
	s_nop 0

; __device__ __forceinline__ void cvt_load(const CvtJob& J, f32x4 (&cv)[8], int wave, int lane) {
;     ...
;     for (int i = 0; i < 8; ++i) { const int k = k0 + wave + 8 * i;
;         cv[i] = nok ? *(const f32x4*)(J.W + (size_t)k * J.N + n0 + 4 * lane) : (f32x4){0.f, 0.f, 0.f, 0.f};
;         if (J.gam) cv[i] = cv[i] * J.gam[k]; }
.LBB0_665:
	s_or_b64 exec, exec, s[62:63]
	s_and_b64 vcc, exec, s[8:9]
	s_cbranch_vccnz .LBB0_667
	s_ashr_i32 s13, s12, 31
	s_lshl_b64 s[34:35], s[12:13], 2
	s_add_u32 s34, s44, s34
	s_addc_u32 s35, s45, s35
	global_load_dword v74, v1, s[34:35] offset:64
	s_nop 0
	s_nop 0
	s_nop 0

; __device__ __forceinline__ void cvt_load(const CvtJob& J, f32x4 (&cv)[8], int wave, int lane) {
;     ...
;     for (int i = 0; i < 8; ++i) { const int k = k0 + wave + 8 * i;
;         cv[i] = nok ? *(const f32x4*)(J.W + (size_t)k * J.N + n0 + 4 * lane) : (f32x4){0.f, 0.f, 0.f, 0.f};
;         if (J.gam) cv[i] = cv[i] * J.gam[k]; }
.LBB0_669:
	s_or_b64 exec, exec, s[62:63]
	s_and_b64 vcc, exec, s[8:9]
	s_cbranch_vccnz .LBB0_671
	s_ashr_i32 s13, s12, 31
	s_lshl_b64 s[34:35], s[12:13], 2
	s_add_u32 s34, s44, s34
	s_addc_u32 s35, s45, s35
	global_load_dword v76, v1, s[34:35] offset:96
	s_nop 0
	s_nop 0
	s_nop 0

; __device__ __forceinline__ void cvt_load(const CvtJob& J, f32x4 (&cv)[8], int wave, int lane) {
;     ...
;     for (int i = 0; i < 8; ++i) { const int k = k0 + wave + 8 * i;
;         cv[i] = nok ? *(const f32x4*)(J.W + (size_t)k * J.N + n0 + 4 * lane) : (f32x4){0.f, 0.f, 0.f, 0.f};
;         if (J.gam) cv[i] = cv[i] * J.gam[k]; }
.LBB0_673:
	s_or_b64 exec, exec, s[62:63]
	s_and_b64 vcc, exec, s[8:9]
	s_cbranch_vccnz .LBB0_675
	s_ashr_i32 s13, s12, 31
	s_lshl_b64 s[34:35], s[12:13], 2
	s_add_u32 s34, s44, s34
	s_addc_u32 s35, s45, s35
	global_load_dword v78, v1, s[34:35] offset:128
	s_nop 0
	s_nop 0
	s_nop 0

; __device__ __forceinline__ void cvt_load(const CvtJob& J, f32x4 (&cv)[8], int wave, int lane) {
;     ...
;     for (int i = 0; i < 8; ++i) { const int k = k0 + wave + 8 * i;
;         cv[i] = nok ? *(const f32x4*)(J.W + (size_t)k * J.N + n0 + 4 * lane) : (f32x4){0.f, 0.f, 0.f, 0.f};
;         if (J.gam) cv[i] = cv[i] * J.gam[k]; }
.LBB0_677:
	s_or_b64 exec, exec, s[62:63]
	s_and_b64 vcc, exec, s[8:9]
	s_cbranch_vccnz .LBB0_679
	s_ashr_i32 s13, s12, 31
	s_lshl_b64 s[34:35], s[12:13], 2
	s_add_u32 s34, s44, s34
	s_addc_u32 s35, s45, s35
	global_load_dword v80, v1, s[34:35] offset:160
	s_nop 0
	s_nop 0
	s_nop 0

; __device__ __forceinline__ void cvt_load(const CvtJob& J, f32x4 (&cv)[8], int wave, int lane) {
;     ...
;     for (int i = 0; i < 8; ++i) { const int k = k0 + wave + 8 * i;
;         cv[i] = nok ? *(const f32x4*)(J.W + (size_t)k * J.N + n0 + 4 * lane) : (f32x4){0.f, 0.f, 0.f, 0.f};
;         if (J.gam) cv[i] = cv[i] * J.gam[k]; }
.LBB0_681:
	s_or_b64 exec, exec, s[62:63]
	s_and_b64 vcc, exec, s[8:9]
	s_cbranch_vccnz .LBB0_683
	s_ashr_i32 s13, s12, 31
	s_lshl_b64 s[34:35], s[12:13], 2
	s_add_u32 s34, s44, s34
	s_addc_u32 s35, s45, s35
	global_load_dword v82, v1, s[34:35] offset:192
	s_nop 0
	s_nop 0
	s_nop 0

; __device__ __forceinline__ void cvt_load(const CvtJob& J, f32x4 (&cv)[8], int wave, int lane) {
;     ...
;     for (int i = 0; i < 8; ++i) { const int k = k0 + wave + 8 * i;
;         cv[i] = nok ? *(const f32x4*)(J.W + (size_t)k * J.N + n0 + 4 * lane) : (f32x4){0.f, 0.f, 0.f, 0.f};
;         if (J.gam) cv[i] = cv[i] * J.gam[k]; }
.LBB0_685:
	s_or_b64 exec, exec, s[62:63]
	s_and_b64 vcc, exec, s[8:9]
	s_cbranch_vccnz .LBB0_687
	s_ashr_i32 s13, s12, 31
	s_lshl_b64 s[6:7], s[12:13], 2
	s_add_u32 s6, s44, s6
	s_addc_u32 s7, s45, s7
	global_load_dword v84, v1, s[6:7] offset:224
	s_nop 0
	s_nop 0
	s_nop 0
